# k17 + DeltaNet output phase loop software-pipelined (next unit's three 16-byte loads issued one iteration ahead)
# baseline (speedup 1.0000x reference)
; __device__ __forceinline__ void phase_dnout(ArgsRef a, const Tb tb, int l) {
;     unsigned char* ws = a.ws;
;     const float* OC = (const float*)(ws + OFF_OCRAW); const bf16_t* Z = (const bf16_t*)(ws + OFF_Z); bf16_t* O = (bf16_t*)(ws + OFF_O);
;     const float* g = a.in[11] + l * 128;
;     const int wv = tb.tid >> 6, lane = tb.tid & 63, sub = lane >> 4, l16 = lane & 15;
;     const int gw = tb.bid * 8 + wv, GW = tb.G * 8;
;     const f32x4 g0 = *(const f32x4*)(g + l16 * 8), g1 = *(const f32x4*)(g + l16 * 8 + 4);
;     for (int u = gw * 4 + sub; u < T_ * 4; u += GW * 4) {
;         const int t = u >> 2, h = u & 3;
;         const float* op = OC + (size_t)t * 512 + h * 128 + l16 * 8;
;         const f32x4 v0 = *(const f32x4*)op, v1 = *(const f32x4*)(op + 4);
;         const u32x4 zz = *(const u32x4*)(Z + (size_t)t * 512 + h * 128 + l16 * 8);
.Ldno_std:
	v_add_u32_e32 v1, s14, v1
	v_and_or_b32 v9, v0, 3, v1
	s_mov_b32 s2, 0x10000
	v_cmp_gt_i32_e32 vcc, s2, v9
	s_and_saveexec_b64 s[2:3], vcc
	s_mov_b32 s13, 0x800000
	s_cbranch_execz .LBB0_347
	v_readlane_b32 s8, v254, 19
	s_waitcnt lgkmcnt(0)
	s_add_u32 s4, s48, 0x9f6a100
	v_readlane_b32 s9, v254, 20
	s_addc_u32 s5, s49, 0
	s_load_dwordx2 s[8:9], s[8:9], 0x58
	s_add_u32 s6, s48, 0xcf6a100
	s_addc_u32 s7, s49, 0
	s_lshl_b32 s10, s50, 7
	s_ashr_i32 s11, s10, 31
	v_lshlrev_b32_e32 v0, 3, v196
	s_lshl_b64 s[10:11], s[10:11], 2
	v_and_b32_e32 v8, 0x78, v0
	s_waitcnt lgkmcnt(0)
	s_add_u32 s8, s8, s10
	s_addc_u32 s9, s9, s11
	v_lshlrev_b32_e32 v4, 2, v8
	global_load_dwordx4 v[0:3], v4, s[8:9]
	s_nop 0
	global_load_dwordx4 v[4:7], v4, s[8:9] offset:16
	v_xor_b32_e32 v10, 8, v236
	v_cmp_lt_i32_e32 vcc, v10, v239
	s_lshl_b32 s10, s56, 5
	s_cmpk_eq_u32 s56, 0x100
	s_cselect_b32 s10, 32, s10
	v_lshlrev_b32_e32 v14, 7, v9
	v_cndmask_b32_e32 v10, v236, v10, vcc
	v_cmp_lt_i32_e32 vcc, v241, v239
	v_lshlrev_b32_e32 v10, 2, v10
	s_lshl_b32 s11, s56, 12
	s_cmpk_eq_u32 s56, 0x100
	s_cselect_b32 s11, 0x1000, s11
	v_cndmask_b32_e32 v11, v236, v241, vcc
	v_cmp_lt_i32_e32 vcc, v240, v239
	v_lshlrev_b32_e32 v11, 2, v11
	s_mov_b64 s[8:9], 0
	v_cndmask_b32_e32 v12, v236, v240, vcc
	v_cmp_lt_i32_e32 vcc, v237, v239
	v_lshlrev_b32_e32 v12, 2, v12
	s_nop 0
	v_cndmask_b32_e32 v13, v236, v237, vcc
	v_lshlrev_b32_e32 v13, 2, v13
	v_lshlrev_b32_e32 v30, 1, v8
	v_mov_b32_e32 v31, v181
	v_ashrrev_i32_e32 v52, 2, v9
	v_ashrrev_i32_e32 v53, 31, v52
	v_lshlrev_b64 v[54:55], 11, v[52:53]
	v_and_b32_e32 v58, 0x180, v14
	v_lshl_add_u64 v[54:55], s[4:5], 0, v[54:55]
	v_lshlrev_b32_e32 v56, 2, v58
	v_mov_b32_e32 v57, 0
	v_lshl_add_u64 v[54:55], v[54:55], 0, v[56:57]
	v_lshlrev_b32_e32 v56, 2, v8
	v_lshl_add_u64 v[54:55], v[54:55], 0, v[56:57]
	global_load_dwordx4 v[40:43], v[54:55], off offset:16
	global_load_dwordx4 v[44:47], v[54:55], off
	v_lshlrev_b64 v[52:53], 10, v[52:53]
	v_lshl_add_u64 v[52:53], s[6:7], 0, v[52:53]
	v_lshlrev_b32_e32 v56, 1, v58
	v_lshl_add_u64 v[52:53], v[52:53], 0, v[56:57]
	v_lshl_add_u64 v[52:53], v[52:53], 0, v[30:31]
	global_load_dwordx4 v[48:51], v[52:53], off
; __device__ __forceinline__ unsigned pk2(float lo, float hi) { const f32x2_t v = {lo, hi}; const bf16x2_t b = __builtin_convertvector(v, bf16x2_t); return __builtin_bit_cast(unsigned, b); }
; __device__ __forceinline__ float bflo(unsigned w) { return __uint_as_float(w << 16); }
; __device__ __forceinline__ float bfhi(unsigned w) { return __uint_as_float(w & 0xffff0000u); }
; __device__ __forceinline__ void phase_dnout(ArgsRef a, const Tb tb, int l) {
;     ...
;     for (int u = gw * 4 + sub; u < T_ * 4; u += GW * 4) {
;         const int t = u >> 2, h = u & 3;
;         const float* op = OC + (size_t)t * 512 + h * 128 + l16 * 8;
;         const f32x4 v0 = *(const f32x4*)op, v1 = *(const f32x4*)(op + 4);
;         const u32x4 zz = *(const u32x4*)(Z + (size_t)t * 512 + h * 128 + l16 * 8);
;         float ss = (v0[0] * v0[0] + v0[1] * v0[1]) + (v0[2] * v0[2] + v0[3] * v0[3]) + (v1[0] * v1[0] + v1[1] * v1[1]) + (v1[2] * v1[2] + v1[3] * v1[3]);
;         ss += __shfl_xor(ss, 8); ss += __shfl_xor(ss, 4); ss += __shfl_xor(ss, 2); ss += __shfl_xor(ss, 1);
;         const float rn = rsqrtf(ss * (1.f / 128.f) + RMS_EPS_);
;         float o[8];
; #pragma unroll
;         for (int i = 0; i < 4; ++i) {
;             const float za = bflo(zz[i]), zb = bfhi(zz[i]);
;             const float va = i < 2 ? v0[2 * i] : v1[2 * i - 4], vb = i < 2 ? v0[2 * i + 1] : v1[2 * i - 3];
;             const float ga = i < 2 ? g0[2 * i] : g1[2 * i - 4], gb = i < 2 ? g0[2 * i + 1] : g1[2 * i - 3];
;             o[2 * i] = va * rn * ga * (za * __builtin_amdgcn_rcpf(1.f + __expf(-za)));
;             o[2 * i + 1] = vb * rn * gb * (zb * __builtin_amdgcn_rcpf(1.f + __expf(-zb)));
;         }
;         u32x4 w; w[0] = pk2(o[0], o[1]); w[1] = pk2(o[2], o[3]); w[2] = pk2(o[4], o[5]); w[3] = pk2(o[6], o[7]);
;         *(u32x4*)(O + (size_t)t * 1024 + 512 + h * 128 + l16 * 8) = w;
;     }
.LBB0_346:
	v_ashrrev_i32_e32 v24, 2, v9
	v_ashrrev_i32_e32 v25, 31, v24
	v_lshlrev_b64 v[28:29], 11, v[24:25]
	v_and_b32_e32 v15, 0x180, v14
	v_lshlrev_b32_e32 v180, 1, v15
	s_waitcnt vmcnt(0)
	v_mov_b32_e32 v16, v40
	v_mov_b32_e32 v17, v41
	v_mov_b32_e32 v18, v42
	v_mov_b32_e32 v19, v43
	v_mov_b32_e32 v20, v44
	v_mov_b32_e32 v21, v45
	v_mov_b32_e32 v22, v46
	v_mov_b32_e32 v23, v47
	v_mov_b32_e32 v24, v48
	v_mov_b32_e32 v25, v49
	v_mov_b32_e32 v26, v50
	v_mov_b32_e32 v27, v51
	v_add_u32_e32 v9, s10, v9
	s_mov_b32 s12, s15
	v_add_u32_e32 v14, s11, v14
	v_ashrrev_i32_e32 v52, 2, v9
	v_ashrrev_i32_e32 v53, 31, v52
	v_lshlrev_b64 v[54:55], 11, v[52:53]
	v_and_b32_e32 v58, 0x180, v14
	v_lshl_add_u64 v[54:55], s[4:5], 0, v[54:55]
	v_lshlrev_b32_e32 v56, 2, v58
	v_mov_b32_e32 v57, 0
	v_lshl_add_u64 v[54:55], v[54:55], 0, v[56:57]
	v_lshlrev_b32_e32 v56, 2, v8
	v_lshl_add_u64 v[54:55], v[54:55], 0, v[56:57]
	global_load_dwordx4 v[40:43], v[54:55], off offset:16
	global_load_dwordx4 v[44:47], v[54:55], off
	v_lshlrev_b64 v[52:53], 10, v[52:53]
	v_lshl_add_u64 v[52:53], s[6:7], 0, v[52:53]
	v_lshlrev_b32_e32 v56, 1, v58
	v_lshl_add_u64 v[52:53], v[52:53], 0, v[56:57]
	v_lshl_add_u64 v[52:53], v[52:53], 0, v[30:31]
	global_load_dwordx4 v[48:51], v[52:53], off
	v_pk_mul_f32 v[32:33], v[22:23], v[22:23]
	v_pk_mul_f32 v[34:35], v[20:21], v[20:21]
	s_nop 0
	v_pk_mov_b32 v[36:37], v[34:35], v[32:33] op_sel:[1,0]
	v_mov_b32_e32 v35, v33
	v_pk_add_f32 v[32:33], v[36:37], v[34:35]
	v_pk_mul_f32 v[34:35], v[18:19], v[18:19]
	v_pk_mul_f32 v[36:37], v[16:17], v[16:17]
	v_mov_b32_e32 v38, v34
	v_mov_b32_e32 v39, v36
	v_mov_b32_e32 v36, v35
	v_pk_add_f32 v[34:35], v[38:39], v[36:37]
	v_add_f32_e32 v15, v32, v33
	v_add_f32_e32 v15, v15, v35
	v_add_f32_e32 v15, v34, v15
	ds_bpermute_b32 v32, v10, v15
	v_lshlrev_b32_e32 v34, 16, v24
	v_and_b32_e32 v35, 0xffff0000, v24
	v_lshlrev_b32_e32 v24, 16, v25
	v_and_b32_e32 v25, 0xffff0000, v25
	s_waitcnt lgkmcnt(0)
	v_add_f32_e32 v15, v15, v32
	ds_bpermute_b32 v32, v11, v15
	s_waitcnt lgkmcnt(0)
	v_add_f32_e32 v15, v15, v32
	ds_bpermute_b32 v32, v12, v15
	s_waitcnt lgkmcnt(0)
	v_add_f32_e32 v15, v15, v32
	ds_bpermute_b32 v32, v13, v15
	s_waitcnt lgkmcnt(0)
	v_add_f32_e32 v15, v15, v32
	v_fmamk_f32 v15, v15, 0x3c000000, v203
	v_cmp_gt_f32_e32 vcc, s13, v15
	v_mul_f32_e32 v32, 0x4b800000, v15
	s_nop 0
	v_cndmask_b32_e32 v15, v15, v32, vcc
	v_rsq_f32_e32 v15, v15
	s_nop 0
	v_mul_f32_e32 v32, 0x45800000, v15
	v_cndmask_b32_e32 v32, v15, v32, vcc
	v_mul_f32_e32 v15, 0xbfb8aa3b, v34
	v_exp_f32_e32 v15, v15
	v_pk_mul_f32 v[20:21], v[20:21], v[32:33] op_sel_hi:[1,0]
	v_pk_mul_f32 v[22:23], v[22:23], v[32:33] op_sel_hi:[1,0]
	v_pk_mul_f32 v[20:21], v[0:1], v[20:21]
	v_add_f32_e32 v15, 1.0, v15
	v_rcp_f32_e32 v36, v15
	v_mul_f32_e32 v15, 0xbfb8aa3b, v35
	v_exp_f32_e32 v15, v15
	v_pk_mul_f32 v[22:23], v[2:3], v[22:23]
	v_pk_mul_f32 v[16:17], v[16:17], v[32:33] op_sel_hi:[1,0]
	v_pk_mul_f32 v[18:19], v[18:19], v[32:33] op_sel_hi:[1,0]
	v_add_f32_e32 v15, 1.0, v15
	v_rcp_f32_e32 v37, v15
	v_mul_f32_e32 v15, 0xbfb8aa3b, v24
	v_exp_f32_e32 v15, v15
	v_pk_mul_f32 v[16:17], v[4:5], v[16:17]
	v_pk_mul_f32 v[34:35], v[36:37], v[34:35]
	v_pk_mul_f32 v[18:19], v[6:7], v[18:19]
	v_add_f32_e32 v15, 1.0, v15
	v_pk_mul_f32 v[20:21], v[34:35], v[20:21]
	v_rcp_f32_e32 v34, v15
	v_mul_f32_e32 v15, 0xbfb8aa3b, v25
	v_exp_f32_e32 v15, v15
	s_nop 0
	v_add_f32_e32 v15, 1.0, v15
	v_rcp_f32_e32 v35, v15
	s_nop 0
	v_pk_mul_f32 v[24:25], v[34:35], v[24:25]
	s_nop 0
	v_pk_mul_f32 v[22:23], v[24:25], v[22:23]
	v_lshlrev_b32_e32 v24, 16, v26
	v_mul_f32_e32 v15, 0xbfb8aa3b, v24
	v_exp_f32_e32 v15, v15
	v_and_b32_e32 v25, 0xffff0000, v26
	v_add_f32_e32 v15, 1.0, v15
	v_rcp_f32_e32 v34, v15
	v_mul_f32_e32 v15, 0xbfb8aa3b, v25
	v_exp_f32_e32 v15, v15
	s_nop 0
	v_add_f32_e32 v15, 1.0, v15
	v_rcp_f32_e32 v35, v15
	s_nop 0
	v_pk_mul_f32 v[24:25], v[34:35], v[24:25]
	s_nop 0
	v_pk_mul_f32 v[24:25], v[24:25], v[16:17]
	v_lshlrev_b32_e32 v16, 16, v27
	v_mul_f32_e32 v15, 0xbfb8aa3b, v16
	v_exp_f32_e32 v15, v15
	v_and_b32_e32 v17, 0xffff0000, v27
	v_add_f32_e32 v15, 1.0, v15
	v_rcp_f32_e32 v26, v15
	v_mul_f32_e32 v15, 0xbfb8aa3b, v17
	v_exp_f32_e32 v15, v15
	s_nop 0
	v_add_f32_e32 v15, 1.0, v15
	v_rcp_f32_e32 v27, v15
	s_nop 0
	v_pk_mul_f32 v[16:17], v[26:27], v[16:17]
	s_nop 0
	v_pk_mul_f32 v[26:27], v[16:17], v[18:19]
	v_cvt_pk_bf16_f32 v16, v20, v21
	v_lshl_add_u64 v[20:21], s[48:49], 0, v[28:29]
	v_lshl_add_u64 v[20:21], v[20:21], 0, v[180:181]
	v_lshl_add_u64 v[20:21], v[20:21], 0, v[30:31]
	v_add_co_u32_e32 v20, vcc, 0xdf6a000, v20
	v_cvt_pk_bf16_f32 v17, v22, v23
	s_nop 0
	v_addc_co_u32_e32 v21, vcc, 0, v21, vcc
	v_cmp_lt_i32_e32 vcc, s12, v9
	v_cvt_pk_bf16_f32 v18, v24, v25
	v_cvt_pk_bf16_f32 v19, v26, v27
	s_or_b64 s[8:9], vcc, s[8:9]
	global_store_dwordx4 v[20:21], v[16:19], off offset:1280
	s_andn2_b64 exec, exec, s[8:9]
	s_cbranch_execnz .LBB0_346
